# XCD-local group barriers: out-proj->LN1, down->LN2, LN2->gate seams wait only for the 4 workgroups of the 256-row block (same XCC verified at run time, else full grid barrier)
# speedup vs baseline: 1.0084x; 1.0084x over previous
_Z4mega4Args:
	s_mov_b64 s[96:97], s[0:1]
	s_mov_b32 s101, 0
	s_mov_b32 s91, s2
	s_load_dwordx4 s[0:3], s[96:97], 0x110
	s_load_dword s94, s[96:97], 0x128
	v_lshl_add_u32 v2, v0, 2, 0
	v_or_b32_e32 v1, 0xfffffe00, v0
	v_add_u32_e32 v2, 0x25000, v2
	s_waitcnt lgkmcnt(0)
	v_writelane_b32 v250, s0, 0
	s_mov_b64 s[4:5], 0
	v_mov_b32_e32 v3, 0
	v_writelane_b32 v250, s1, 1
	v_writelane_b32 v250, s2, 2
	v_writelane_b32 v250, s3, 3
	s_add_u32 s0, s96, 0x128
	s_addc_u32 s1, s97, 0
	v_writelane_b32 v250, s0, 4
	s_nop 1
	v_writelane_b32 v250, s1, 5
	v_readfirstlane_b32 s1, v0
.LBB0_1:
	v_add_co_u32_e32 v1, vcc, 0x200, v1
	s_xor_b64 s[2:3], vcc, -1
	s_and_b64 s[2:3], exec, s[2:3]
	ds_write_b32 v2, v3
	s_or_b64 s[4:5], s[2:3], s[4:5]
	v_add_u32_e32 v2, 0x800, v2
	s_andn2_b64 exec, exec, s[4:5]
	s_cbranch_execnz .LBB0_1
	s_or_b64 exec, exec, s[4:5]
	s_load_dwordx4 s[4:7], s[96:97], 0x110
	s_waitcnt lgkmcnt(0)
	s_barrier
	s_getreg_b32 s0, hwreg(HW_REG_XCC_ID, 0, 4)
	s_add_u32 s14, s4, 0x4000
	s_addc_u32 s15, s5, 0
	s_and_b32 s0, s0, 15
	v_cmp_eq_u32_e32 vcc, 0, v0
	s_and_saveexec_b64 s[4:5], vcc
	s_cbranch_execz .LBB0_5
	s_mov_b64 s[6:7], exec
	v_mbcnt_lo_u32_b32 v0, s6, 0
	v_mbcnt_hi_u32_b32 v0, s7, v0
	v_cmp_eq_u32_e32 vcc, 0, v0
	s_and_b64 s[2:3], exec, vcc
	s_mov_b64 exec, s[2:3]
	s_cbranch_execz .LBB0_5
	s_lshl_b32 s2, s0, 8
	s_bcnt1_i32_b64 s3, s[6:7]
	v_mov_b32_e32 v0, s2
	v_mov_b32_e32 v1, s3
	global_atomic_add v0, v1, s[14:15] offset:1024
	s_lshl_b32 s2, s91, 2
	s_add_i32 s2, s2, 0x5c000
	s_add_i32 s3, s0, 1
	s_nop 1
	v_mov_b32_e32 v0, s2
	v_mov_b32_e32 v1, s3
	global_store_dword v0, v1, s[14:15]

.LBB0_1900:
	v_readlane_b32 s0, v253, 37
	v_readlane_b32 s16, v250, 0
	s_or_b32 s0, s0, 10
	v_readlane_b32 s19, v250, 3
	s_cmp_ge_i32 s0, s19
	v_readlane_b32 s17, v250, 1
	v_readlane_b32 s18, v250, 2
	s_cbranch_scc1 .LBB0_1956
	s_waitcnt vmcnt(0)
	v_readlane_b32 s2, v253, 40
	v_readlane_b32 s3, v253, 41
	s_and_b64 vcc, exec, s[2:3]
	s_waitcnt vmcnt(0) lgkmcnt(0)
	s_barrier
	s_cbranch_vccnz .LBB0_1955
	s_cmp_lg_u32 s101, 0
	s_cbranch_scc1 .Lmy_gchk_0
	s_mov_b32 s101, 2
	s_cmp_lg_u32 s94, 0x100
	s_cbranch_scc1 .Lmy_gchk_0
	v_readlane_b32 s8, v250, 0
	v_readlane_b32 s9, v250, 1
	s_mov_b32 s2, -1
	v_mbcnt_lo_u32_b32 v0, s2, 0
	v_mbcnt_hi_u32_b32 v0, s2, v0
	v_lshlrev_b32_e32 v0, 2, v0
	s_add_u32 s8, s8, 0x60000
	s_addc_u32 s9, s9, 0
	global_load_dword v1, v0, s[8:9] sc0 sc1
	global_load_dword v2, v0, s[8:9] offset:256 sc0 sc1
	global_load_dword v3, v0, s[8:9] offset:512 sc0 sc1
	global_load_dword v4, v0, s[8:9] offset:768 sc0 sc1
	s_waitcnt vmcnt(0)
	v_cmp_ne_u32_e32 vcc, 0, v1
	v_cmp_eq_u32_e64 s[2:3], v1, v2
	v_cmp_eq_u32_e64 s[12:13], v1, v3
	s_and_b64 s[2:3], s[2:3], vcc
	v_cmp_eq_u32_e64 s[8:9], v1, v4
	s_and_b64 s[2:3], s[2:3], s[12:13]
	s_and_b64 s[2:3], s[2:3], s[8:9]
	s_cmp_eq_u64 s[2:3], -1
	s_cbranch_scc0 .Lmy_gchk_0
	s_mov_b32 s101, 1
.Lmy_gchk_0:
	s_mov_b32 s2, -1
	s_nop 0
	v_mbcnt_lo_u32_b32 v0, s2, 0
	v_mbcnt_hi_u32_b32 v0, s2, v0
	s_nop 0
	v_cmp_eq_u32_e32 vcc, 0, v0
	s_and_saveexec_b64 s[16:17], vcc
	s_cbranch_execz .LBB0_1954
	s_cmp_lg_u32 s101, 1
	s_cbranch_scc1 .Lmy_gfull_0
	v_readlane_b32 s2, v253, 37
	v_readlane_b32 s3, v250, 7
	v_readlane_b32 s8, v250, 0
	v_readlane_b32 s9, v250, 1
	s_lshl_b32 s2, s2, 10
	s_add_i32 s2, s2, 0x0
	s_and_b32 s3, s3, 63
	s_lshl_b32 s3, s3, 6
	s_add_i32 s2, s2, s3
	s_add_u32 s8, s8, 0x70000
	s_addc_u32 s9, s9, 0
	v_mov_b32_e32 v0, s2
	v_mov_b32_e32 v1, 1
	s_waitcnt vmcnt(0) lgkmcnt(0)
	global_atomic_add v0, v1, s[8:9]
	s_mov_b32 s2, 0
.Lmy_gspin_0:
	global_load_dword v2, v0, s[8:9] sc1
	s_waitcnt vmcnt(0)
	v_readfirstlane_b32 s3, v2
	s_cmp_ge_u32 s3, 4
	s_cbranch_scc1 .Lmy_gdone_0
	s_sleep 1
	s_add_i32 s2, s2, 1
	s_cmp_lt_u32 s2, 0x4000
	s_cbranch_scc1 .Lmy_gspin_0
.Lmy_gdone_0:
	buffer_inv sc1
	s_waitcnt vmcnt(0)
	s_branch .LBB0_1954
.Lmy_gfull_0:
	v_readlane_b32 s2, v252, 30
	s_waitcnt vmcnt(0) expcnt(0) lgkmcnt(0)
	s_nop 0
	v_mov_b32_e32 v0, s2
	ds_read_b32 v2, v0
	v_readlane_b32 s2, v252, 31
	s_waitcnt lgkmcnt(0)
	v_cmp_ne_u32_e32 vcc, 0, v2
	v_mov_b32_e32 v0, s2
	ds_read_b32 v0, v0
	s_cbranch_vccnz .LBB0_1918
	v_readlane_b32 s8, v250, 4
	v_readlane_b32 s9, v250, 5
	s_load_dwordx2 s[2:3], s[8:9], 0x4
	s_waitcnt lgkmcnt(0)
	s_mul_i32 s2, s2, s94
	s_mul_i32 s2, s2, s3
	s_mov_b32 s3, 1
	s_branch .LBB0_1906

.LBB0_2249:
	v_readlane_b32 s0, v253, 37
	v_readlane_b32 s16, v250, 0
	s_or_b32 s0, s0, 14
	v_readlane_b32 s19, v250, 3
	s_cmp_ge_i32 s0, s19
	v_readlane_b32 s17, v250, 1
	v_readlane_b32 s18, v250, 2
	s_cbranch_scc1 .LBB0_2305
	s_waitcnt vmcnt(0)
	v_readlane_b32 s2, v253, 40
	v_readlane_b32 s3, v253, 41
	s_and_b64 vcc, exec, s[2:3]
	s_waitcnt vmcnt(0) lgkmcnt(0)
	s_barrier
	s_cbranch_vccnz .LBB0_2304
	s_cmp_lg_u32 s101, 0
	s_cbranch_scc1 .Lmy_gchk_1
	s_mov_b32 s101, 2
	s_cmp_lg_u32 s94, 0x100
	s_cbranch_scc1 .Lmy_gchk_1
	v_readlane_b32 s8, v250, 0
	v_readlane_b32 s9, v250, 1
	s_mov_b32 s2, -1
	v_mbcnt_lo_u32_b32 v0, s2, 0
	v_mbcnt_hi_u32_b32 v0, s2, v0
	v_lshlrev_b32_e32 v0, 2, v0
	s_add_u32 s8, s8, 0x60000
	s_addc_u32 s9, s9, 0
	global_load_dword v1, v0, s[8:9] sc0 sc1
	global_load_dword v2, v0, s[8:9] offset:256 sc0 sc1
	global_load_dword v3, v0, s[8:9] offset:512 sc0 sc1
	global_load_dword v4, v0, s[8:9] offset:768 sc0 sc1
	s_waitcnt vmcnt(0)
	v_cmp_ne_u32_e32 vcc, 0, v1
	v_cmp_eq_u32_e64 s[2:3], v1, v2
	v_cmp_eq_u32_e64 s[12:13], v1, v3
	s_and_b64 s[2:3], s[2:3], vcc
	v_cmp_eq_u32_e64 s[8:9], v1, v4
	s_and_b64 s[2:3], s[2:3], s[12:13]
	s_and_b64 s[2:3], s[2:3], s[8:9]
	s_cmp_eq_u64 s[2:3], -1
	s_cbranch_scc0 .Lmy_gchk_1
	s_mov_b32 s101, 1
.Lmy_gchk_1:
	s_mov_b32 s2, -1
	s_nop 0
	v_mbcnt_lo_u32_b32 v0, s2, 0
	v_mbcnt_hi_u32_b32 v0, s2, v0
	s_nop 0
	v_cmp_eq_u32_e32 vcc, 0, v0
	s_and_saveexec_b64 s[16:17], vcc
	s_cbranch_execz .LBB0_2303
	s_cmp_lg_u32 s101, 1
	s_cbranch_scc1 .Lmy_gfull_1
	v_readlane_b32 s2, v253, 37
	v_readlane_b32 s3, v250, 7
	v_readlane_b32 s8, v250, 0
	v_readlane_b32 s9, v250, 1
	s_lshl_b32 s2, s2, 10
	s_add_i32 s2, s2, 0x1000
	s_and_b32 s3, s3, 63
	s_lshl_b32 s3, s3, 6
	s_add_i32 s2, s2, s3
	s_add_u32 s8, s8, 0x70000
	s_addc_u32 s9, s9, 0
	v_mov_b32_e32 v0, s2
	v_mov_b32_e32 v1, 1
	s_waitcnt vmcnt(0) lgkmcnt(0)
	global_atomic_add v0, v1, s[8:9]
	s_mov_b32 s2, 0

.LBB0_2327:
	v_readlane_b32 s0, v253, 37
	v_readlane_b32 s16, v250, 0
	s_or_b32 s0, s0, 15
	v_readlane_b32 s19, v250, 3
	s_cmp_ge_i32 s0, s19
	v_readlane_b32 s17, v250, 1
	v_readlane_b32 s18, v250, 2
	s_cbranch_scc1 .LBB0_2383
	s_waitcnt vmcnt(0)
	v_readlane_b32 s2, v253, 40
	v_readlane_b32 s3, v253, 41
	s_and_b64 vcc, exec, s[2:3]
	s_waitcnt vmcnt(0) lgkmcnt(0)
	s_barrier
	s_cbranch_vccnz .LBB0_2382
	s_cmp_lg_u32 s101, 0
	s_cbranch_scc1 .Lmy_gchk_2
	s_mov_b32 s101, 2
	s_cmp_lg_u32 s94, 0x100
	s_cbranch_scc1 .Lmy_gchk_2
	v_readlane_b32 s8, v250, 0
	v_readlane_b32 s9, v250, 1
	s_mov_b32 s2, -1
	v_mbcnt_lo_u32_b32 v0, s2, 0
	v_mbcnt_hi_u32_b32 v0, s2, v0
	v_lshlrev_b32_e32 v0, 2, v0
	s_add_u32 s8, s8, 0x60000
	s_addc_u32 s9, s9, 0
	global_load_dword v1, v0, s[8:9] sc0 sc1
	global_load_dword v2, v0, s[8:9] offset:256 sc0 sc1
	global_load_dword v3, v0, s[8:9] offset:512 sc0 sc1
	global_load_dword v4, v0, s[8:9] offset:768 sc0 sc1
	s_waitcnt vmcnt(0)
	v_cmp_ne_u32_e32 vcc, 0, v1
	v_cmp_eq_u32_e64 s[2:3], v1, v2
	v_cmp_eq_u32_e64 s[12:13], v1, v3
	s_and_b64 s[2:3], s[2:3], vcc
	v_cmp_eq_u32_e64 s[8:9], v1, v4
	s_and_b64 s[2:3], s[2:3], s[12:13]
	s_and_b64 s[2:3], s[2:3], s[8:9]
	s_cmp_eq_u64 s[2:3], -1
	s_cbranch_scc0 .Lmy_gchk_2
	s_mov_b32 s101, 1
.Lmy_gchk_2:
	s_mov_b32 s2, -1
	s_nop 0
	v_mbcnt_lo_u32_b32 v0, s2, 0
	v_mbcnt_hi_u32_b32 v0, s2, v0
	s_nop 0
	v_cmp_eq_u32_e32 vcc, 0, v0
	s_and_saveexec_b64 s[16:17], vcc
	s_cbranch_execz .LBB0_2381
	s_cmp_lg_u32 s101, 1
	s_cbranch_scc1 .Lmy_gfull_2
	v_readlane_b32 s2, v253, 37
	v_readlane_b32 s3, v250, 7
	v_readlane_b32 s8, v250, 0
	v_readlane_b32 s9, v250, 1
	s_lshl_b32 s2, s2, 10
	s_add_i32 s2, s2, 0x2000
	s_and_b32 s3, s3, 63
	s_lshl_b32 s3, s3, 6
	s_add_i32 s2, s2, s3
	s_add_u32 s8, s8, 0x70000
	s_addc_u32 s9, s9, 0
	v_mov_b32_e32 v0, s2
	v_mov_b32_e32 v1, 1
	s_waitcnt vmcnt(0) lgkmcnt(0)
	global_atomic_add v0, v1, s[8:9]
	s_mov_b32 s2, 0
